# v61 + helper progress-flag polls executed by 4 lanes only (exec masked around the spin loop)
# baseline (speedup 1.0000x reference)
.LBB0_725:
	s_waitcnt lgkmcnt(0)
	s_add_i32 s64, s46, 4
	v_mov_b32_e32 v248, s64
	ds_write_b32 v247, v248
	s_mov_b64 exec, 15

.Lhflag_go_4:
	s_mov_b64 exec, -1
	s_add_i32 s46, s46, 4
	s_add_i32 s45, s45, 64
	s_cmpk_lt_u32 s23, 0x1fc
	s_mov_b32 s49, s20
	s_cbranch_scc0 .LBB0_830

.LBB0_752:
	s_waitcnt lgkmcnt(0)
	s_add_i32 s64, s46, 1
	v_mov_b32_e32 v248, s64
	ds_write_b32 v247, v248
	s_mov_b64 exec, 15

.Lhflag_go_1:
	s_mov_b64 exec, -1
	s_min_u32 s15, s23, 0x1fa
	s_and_b64 vcc, exec, s[4:5]
	s_mov_b64 s[40:41], -1
	s_cbranch_vccnz .LBB0_754
	v_lshl_add_u32 v10, s15, 4, v167
	v_sub_u32_e32 v106, 0x1faf, v10
	s_mov_b64 s[40:41], 0

.LBB0_778:
	s_waitcnt lgkmcnt(0)
	s_add_i32 s64, s46, 2
	v_mov_b32_e32 v248, s64
	ds_write_b32 v247, v248
	s_mov_b64 exec, 15

.Lhflag_go_2:
	s_mov_b64 exec, -1
	s_min_u32 s15, s23, 0x1f9
	s_and_b64 vcc, exec, s[4:5]
	s_mov_b64 s[52:53], -1
	s_cbranch_vccnz .LBB0_780
	v_lshl_add_u32 v18, s15, 4, v167
	v_sub_u32_e32 v106, 0x1f9f, v18
	s_mov_b64 s[52:53], 0

.LBB0_805:
	s_waitcnt lgkmcnt(0)
	s_add_i32 s64, s46, 3
	v_mov_b32_e32 v248, s64
	ds_write_b32 v247, v248
	s_mov_b64 exec, 15

.Lhflag_go_3:
	s_mov_b64 exec, -1
	s_min_u32 s15, s23, 0x1f8
	s_and_b64 vcc, exec, s[4:5]
	s_mov_b64 s[42:43], -1
	s_cbranch_vccnz .LBB0_807
	v_lshl_add_u32 v90, s15, 4, v167
	v_sub_u32_e32 v106, 0x1f8f, v90
	s_mov_b64 s[42:43], 0
